# adaLN tile reduction: the loop-invariant bias word is loaded once before the reduction loop instead of load+wait in each of its 4-5 iterations; on top of version 43
# speedup vs baseline: 1.0056x; 1.0056x over previous
.LBB0_139:
	s_ashr_i32 s6, s16, 2
	s_mul_hi_i32 s7, s6, 0x2aaaaaab
	s_lshr_b32 s8, s7, 31
	s_lshr_b32 s7, s7, 3
	s_add_i32 s7, s7, s8
	s_mul_i32 s7, s7, 48
	s_sub_i32 s6, s6, s7
	s_mul_hi_i32 s7, s16, 0x2aaaaaab
	s_lshr_b32 s8, s7, 31
	s_ashr_i32 s14, s7, 5
	s_add_i32 s14, s14, s8
	v_readlane_b32 s36, v241, 18
	s_and_b32 s12, s16, 3
	s_mul_i32 s8, s14, 0xc00000
	v_readlane_b32 s40, v241, 22
	s_mul_hi_i32 s7, s14, 0xc00000
	v_readlane_b32 s41, v241, 23
	s_add_u32 s8, s40, s8
	s_addc_u32 s7, s41, s7
	s_lshl_b32 s9, s12, 8
	v_or_b32_sdwa v2, s9, v1 dst_sel:DWORD dst_unused:UNUSED_PAD src0_sel:DWORD src1_sel:BYTE_0
	v_lshlrev_b32_e32 v128, 2, v2
	v_lshl_add_u64 v[2:3], v[130:131], 0, v[128:129]
	s_barrier
	global_load_dword v4, v[2:3], off
	v_lshl_add_u64 v[2:3], v[132:133], 0, v[128:129]
	global_load_dword v5, v[2:3], off
	v_lshl_add_u64 v[2:3], v[2:3], 0, s[0:1]
	flat_load_dword v6, v[2:3]
	v_lshl_add_u64 v[2:3], v[2:3], 0, s[0:1]
	flat_load_dword v7, v[2:3]
	v_lshl_add_u64 v[2:3], v[2:3], 0, s[0:1]
	flat_load_dword v8, v[2:3]
	v_lshl_add_u64 v[2:3], v[2:3], 0, s[0:1]
	flat_load_dword v9, v[2:3]
	v_lshl_add_u64 v[2:3], v[2:3], 0, s[0:1]
	flat_load_dword v10, v[2:3]
	v_lshl_add_u64 v[2:3], v[2:3], 0, s[0:1]
	flat_load_dword v11, v[2:3]
	v_lshl_add_u64 v[2:3], v[2:3], 0, s[0:1]
	flat_load_dword v12, v[2:3]
	v_lshl_add_u64 v[2:3], v[2:3], 0, s[0:1]
	flat_load_dword v13, v[2:3]
	v_lshl_add_u64 v[2:3], v[2:3], 0, s[0:1]
	flat_load_dword v14, v[2:3]
	v_lshl_add_u64 v[2:3], v[2:3], 0, s[0:1]
	flat_load_dword v15, v[2:3]
	v_lshl_add_u64 v[2:3], v[2:3], 0, s[0:1]
	flat_load_dword v16, v[2:3]
	v_lshl_add_u64 v[2:3], v[2:3], 0, s[0:1]
	flat_load_dword v17, v[2:3]
	v_lshl_add_u64 v[2:3], v[2:3], 0, s[0:1]
	flat_load_dword v18, v[2:3]
	v_lshl_add_u64 v[2:3], v[2:3], 0, s[0:1]
	flat_load_dword v19, v[2:3]
	v_lshl_add_u64 v[2:3], v[2:3], 0, s[0:1]
	flat_load_dword v20, v[2:3]
	v_lshl_add_u64 v[2:3], v[2:3], 0, s[0:1]
	s_add_i32 s9, s9, s17
	s_mul_hi_i32 s13, s9, 0x3000
	s_mulk_i32 s9, 0x3000
	s_add_u32 s15, s8, s9
	s_addc_u32 s13, s7, s13
	s_lshl_b32 s6, s6, 6
	s_ashr_i32 s7, s6, 31
	s_lshl_b64 s[8:9], s[6:7], 2
	s_add_u32 s8, s15, s8
	s_addc_u32 s9, s13, s9
	global_load_dword v179, v134, s[8:9]
	v_readlane_b32 s37, v241, 19
	v_readlane_b32 s38, v241, 20
	v_readlane_b32 s39, v241, 21
	v_readlane_b32 s42, v241, 24
	v_readlane_b32 s43, v241, 25
	v_readlane_b32 s44, v241, 26
	v_readlane_b32 s45, v241, 27
	v_readlane_b32 s46, v241, 28
	v_readlane_b32 s47, v241, 29
	v_readlane_b32 s48, v241, 30
	v_readlane_b32 s49, v241, 31
	v_readlane_b32 s50, v241, 32
	v_readlane_b32 s51, v241, 33
	s_waitcnt vmcnt(0)
	v_mul_f32_e32 v2, 0xbfb8aa3b, v4
	v_exp_f32_e32 v2, v2
	v_mul_f32_e32 v3, 0xbfb8aa3b, v5
	v_exp_f32_e32 v3, v3
	v_add_f32_e32 v2, 1.0, v2
	v_rcp_f32_e32 v2, v2
	s_waitcnt lgkmcnt(0)
	v_mul_f32_e32 v21, 0xbfb8aa3b, v6
	v_mul_f32_e32 v22, 0xbfb8aa3b, v7
	v_exp_f32_e32 v22, v22
	v_add_f32_e32 v3, 1.0, v3
	v_exp_f32_e32 v21, v21
	v_rcp_f32_e32 v3, v3
	v_add_f32_e32 v22, 1.0, v22
	v_mul_f32_e32 v2, v4, v2
	v_rcp_f32_e32 v4, v22
	v_add_f32_e32 v21, 1.0, v21
	v_mul_f32_e32 v3, v5, v3
	v_mul_f32_e32 v23, 0xbfb8aa3b, v8
	v_rcp_f32_e32 v21, v21
	ds_write2st64_b32 v127, v2, v3 offset1:8
	v_mul_f32_e32 v3, v7, v4
	v_mul_f32_e32 v4, 0xbfb8aa3b, v9
	v_exp_f32_e32 v23, v23
	v_exp_f32_e32 v4, v4
	v_mul_f32_e32 v2, v6, v21
	ds_write2st64_b32 v127, v2, v3 offset0:16 offset1:24
	v_add_f32_e32 v2, 1.0, v23
	v_add_f32_e32 v3, 1.0, v4
	v_rcp_f32_e32 v2, v2
	v_rcp_f32_e32 v3, v3
	v_mul_f32_e32 v4, 0xbfb8aa3b, v10
	v_exp_f32_e32 v4, v4
	v_mul_f32_e32 v2, v8, v2
	v_mul_f32_e32 v3, v9, v3
	ds_write2st64_b32 v127, v2, v3 offset0:32 offset1:40
	v_mul_f32_e32 v3, 0xbfb8aa3b, v11
	v_add_f32_e32 v2, 1.0, v4
	v_exp_f32_e32 v3, v3
	v_mul_f32_e32 v4, 0xbfb8aa3b, v12
	v_exp_f32_e32 v4, v4
	v_rcp_f32_e32 v2, v2
	v_add_f32_e32 v3, 1.0, v3
	v_rcp_f32_e32 v3, v3
	v_add_f32_e32 v4, 1.0, v4
	v_mul_f32_e32 v5, 0xbfb8aa3b, v13
	v_rcp_f32_e32 v4, v4
	v_exp_f32_e32 v5, v5
	v_mul_f32_e32 v2, v10, v2
	v_mul_f32_e32 v3, v11, v3
	ds_write2st64_b32 v127, v2, v3 offset0:48 offset1:56
	v_mul_f32_e32 v2, v12, v4
	v_add_f32_e32 v3, 1.0, v5
	v_mul_f32_e32 v4, 0xbfb8aa3b, v14
	v_mul_f32_e32 v5, 0xbfb8aa3b, v15
	v_exp_f32_e32 v4, v4
	v_exp_f32_e32 v5, v5
	v_rcp_f32_e32 v3, v3
	v_add_f32_e32 v4, 1.0, v4
	v_add_f32_e32 v5, 1.0, v5
	v_rcp_f32_e32 v4, v4
	v_rcp_f32_e32 v5, v5
	v_mul_f32_e32 v3, v13, v3
	ds_write2st64_b32 v127, v2, v3 offset0:64 offset1:72
	v_mul_f32_e32 v2, v14, v4
	v_mul_f32_e32 v3, v15, v5
	v_mul_f32_e32 v4, 0xbfb8aa3b, v16
	v_mul_f32_e32 v5, 0xbfb8aa3b, v17
	v_exp_f32_e32 v4, v4
	v_exp_f32_e32 v5, v5
	ds_write2st64_b32 v127, v2, v3 offset0:80 offset1:88
	v_add_f32_e32 v2, 1.0, v4
	v_add_f32_e32 v3, 1.0, v5
	v_rcp_f32_e32 v2, v2
	v_rcp_f32_e32 v3, v3
	v_mul_f32_e32 v4, 0xbfb8aa3b, v18
	v_exp_f32_e32 v4, v4
	v_mul_f32_e32 v2, v16, v2
	v_mul_f32_e32 v3, v17, v3
	ds_write2st64_b32 v127, v2, v3 offset0:96 offset1:104
	v_mul_f32_e32 v3, 0xbfb8aa3b, v19
	v_add_f32_e32 v2, 1.0, v4
	v_exp_f32_e32 v3, v3
	v_mul_f32_e32 v4, 0xbfb8aa3b, v20
	v_exp_f32_e32 v4, v4
	v_rcp_f32_e32 v2, v2
	v_add_f32_e32 v3, 1.0, v3
	v_rcp_f32_e32 v3, v3
	v_add_f32_e32 v4, 1.0, v4
	v_rcp_f32_e32 v4, v4
	v_mul_f32_e32 v2, v18, v2
	v_mul_f32_e32 v3, v19, v3
	ds_write2st64_b32 v127, v2, v3 offset0:112 offset1:120
	v_mul_f32_e32 v2, v20, v4
	ds_write_b32 v127, v2 offset:32768
	v_lshl_add_u64 v[2:3], s[8:9], 0, v[134:135]
	v_lshl_add_u64 v[2:3], v[2:3], 0, s[2:3]
	flat_load_dword v200, v[2:3]
	v_lshl_add_u64 v[2:3], v[2:3], 0, s[2:3]
	flat_load_dword v201, v[2:3]
	v_lshl_add_u64 v[2:3], v[2:3], 0, s[2:3]
	flat_load_dword v202, v[2:3]
	v_lshl_add_u64 v[2:3], v[2:3], 0, s[2:3]
	flat_load_dword v199, v[2:3]
	v_lshl_add_u64 v[2:3], v[2:3], 0, s[2:3]
	flat_load_dword v198, v[2:3]
	v_lshl_add_u64 v[2:3], v[2:3], 0, s[2:3]
	flat_load_dword v197, v[2:3]
	v_lshl_add_u64 v[2:3], v[2:3], 0, s[2:3]
	flat_load_dword v196, v[2:3]
	v_lshl_add_u64 v[2:3], v[2:3], 0, s[2:3]
	flat_load_dword v192, v[2:3]
	v_lshl_add_u64 v[2:3], v[2:3], 0, s[2:3]
	flat_load_dword v193, v[2:3]
	v_lshl_add_u64 v[2:3], v[2:3], 0, s[2:3]
	flat_load_dword v194, v[2:3]
	v_lshl_add_u64 v[2:3], v[2:3], 0, s[2:3]
	flat_load_dword v195, v[2:3]
	v_lshl_add_u64 v[2:3], v[2:3], 0, s[2:3]
	flat_load_dword v191, v[2:3]
	v_lshl_add_u64 v[2:3], v[2:3], 0, s[2:3]
	flat_load_dword v190, v[2:3]
	v_lshl_add_u64 v[2:3], v[2:3], 0, s[2:3]
	flat_load_dword v189, v[2:3]
	v_lshl_add_u64 v[2:3], v[2:3], 0, s[2:3]
	flat_load_dword v188, v[2:3]
	v_lshl_add_u64 v[2:3], v[2:3], 0, s[2:3]
	flat_load_dword v184, v[2:3]
	v_lshl_add_u64 v[2:3], v[2:3], 0, s[2:3]
	flat_load_dword v185, v[2:3]
	v_lshl_add_u64 v[2:3], v[2:3], 0, s[2:3]
	flat_load_dword v186, v[2:3]
	v_lshl_add_u64 v[2:3], v[2:3], 0, s[2:3]
	flat_load_dword v187, v[2:3]
	v_lshl_add_u64 v[2:3], v[2:3], 0, s[2:3]
	flat_load_dword v183, v[2:3]
	v_lshl_add_u64 v[2:3], v[2:3], 0, s[2:3]
	flat_load_dword v182, v[2:3]
	v_lshl_add_u64 v[2:3], v[2:3], 0, s[2:3]
	flat_load_dword v181, v[2:3]
	v_lshl_add_u64 v[2:3], v[2:3], 0, s[2:3]
	flat_load_dword v180, v[2:3]
	v_lshl_add_u64 v[2:3], v[2:3], 0, s[2:3]
	flat_load_dword v143, v[2:3]
	v_lshl_add_u64 v[2:3], v[2:3], 0, s[2:3]
	flat_load_dword v144, v[2:3]
	v_lshl_add_u64 v[2:3], v[2:3], 0, s[2:3]
	flat_load_dword v145, v[2:3]
	v_lshl_add_u64 v[2:3], v[2:3], 0, s[2:3]
	flat_load_dword v146, v[2:3]
	v_lshl_add_u64 v[2:3], v[2:3], 0, s[2:3]
	flat_load_dword v142, v[2:3]
	v_lshl_add_u64 v[2:3], v[2:3], 0, s[2:3]
	flat_load_dword v141, v[2:3]
	v_lshl_add_u64 v[2:3], v[2:3], 0, s[2:3]
	flat_load_dword v140, v[2:3]
	v_lshl_add_u64 v[2:3], v[2:3], 0, s[2:3]
	flat_load_dword v128, v[2:3]
	v_lshl_add_u64 v[2:3], v[2:3], 0, s[2:3]
	s_waitcnt lgkmcnt(0)
	s_barrier
	ds_read_b128 v[14:17], v137
	ds_read_b128 v[10:13], v137 offset:1024
	ds_read_b128 v[2:5], v137 offset:16
	ds_read_b128 v[6:9], v137 offset:2048
	ds_read_b128 v[26:29], v137 offset:1040
	ds_read_b128 v[18:21], v137 offset:3072
	ds_read_b128 v[30:33], v137 offset:2064
	ds_read_b128 v[22:25], v137 offset:4096
	ds_read_b128 v[34:37], v137 offset:3088
	ds_read_b128 v[74:77], v137 offset:5120
	ds_read_b128 v[38:41], v137 offset:4112
	ds_read_b128 v[78:81], v137 offset:6144
	ds_read_b128 v[42:45], v137 offset:5136
	ds_read_b128 v[82:85], v137 offset:7168
	ds_read_b128 v[46:49], v137 offset:6160
	ds_read_b128 v[86:89], v137 offset:8192
	ds_read_b128 v[50:53], v137 offset:7184
	ds_read_b128 v[90:93], v137 offset:9216
	ds_read_b128 v[54:57], v137 offset:8208
	ds_read_b128 v[94:97], v137 offset:10240
	ds_read_b128 v[58:61], v137 offset:9232
	s_waitcnt lgkmcnt(0)
	v_fma_f32 v148, v179, v6, 0
	v_fma_f32 v153, v179, v82, 0
	ds_read_b128 v[98:101], v137 offset:11264
	ds_read_b128 v[102:105], v137 offset:12288
	ds_read_b128 v[62:65], v137 offset:10256
	v_fma_f32 v139, v179, v14, 0
	v_fma_f32 v147, v179, v10, 0
	v_fma_f32 v149, v179, v18, 0
	v_fma_f32 v150, v179, v22, 0
	v_fma_f32 v156, v179, v94, 0
	s_waitcnt vmcnt(0)
	v_fmac_f32_e32 v148, v200, v7
	v_fmac_f32_e32 v153, v200, v83
	v_fmac_f32_e32 v139, v200, v15
	v_fmac_f32_e32 v147, v200, v11
	v_fmac_f32_e32 v148, v201, v8
	v_fmac_f32_e32 v149, v200, v19
	v_fmac_f32_e32 v150, v200, v23
	v_fmac_f32_e32 v153, v201, v84
	v_fmac_f32_e32 v156, v200, v95
	ds_read_b128 v[66:69], v137 offset:11280
	ds_read_b128 v[70:73], v137 offset:12304
	s_waitcnt lgkmcnt(4)
	v_fma_f32 v157, v179, v98, 0
	v_fmac_f32_e32 v139, v201, v16
	v_fmac_f32_e32 v147, v201, v12
	v_fmac_f32_e32 v148, v202, v9
	ds_read_b128 v[106:109], v137 offset:13312
	ds_read_b128 v[6:9], v137 offset:13328
	v_fmac_f32_e32 v149, v201, v20
	v_fmac_f32_e32 v150, v201, v24
	v_fmac_f32_e32 v153, v202, v85
	ds_read_b128 v[82:85], v137 offset:16384
	v_fmac_f32_e32 v156, v201, v96
	v_fmac_f32_e32 v139, v202, v17
	v_fmac_f32_e32 v147, v202, v13
	v_fmac_f32_e32 v149, v202, v21
	v_fmac_f32_e32 v150, v202, v25
	ds_read_b128 v[110:113], v137 offset:14336
	ds_read_b128 v[14:17], v137 offset:14352
	ds_read_b128 v[114:117], v137 offset:15360
	ds_read_b128 v[10:13], v137 offset:15376
	ds_read_b128 v[18:21], v137 offset:16400
	v_fmac_f32_e32 v156, v202, v97
	v_fmac_f32_e32 v157, v200, v99
	ds_read_b128 v[94:97], v137 offset:17408
	ds_read_b128 v[22:25], v137 offset:17424
	v_fma_f32 v154, v179, v86, 0
	v_fma_f32 v155, v179, v90, 0
	v_fmac_f32_e32 v157, v201, v100
	v_fmac_f32_e32 v154, v200, v87
	v_fmac_f32_e32 v155, v200, v91
	v_fmac_f32_e32 v157, v202, v101
	ds_read_b128 v[98:101], v137 offset:20480
	v_fmac_f32_e32 v154, v201, v88
	v_fmac_f32_e32 v155, v201, v92
	s_waitcnt lgkmcnt(14)
	v_fma_f32 v158, v179, v102, 0
	v_fmac_f32_e32 v154, v202, v89
	v_fmac_f32_e32 v155, v202, v93
	s_waitcnt lgkmcnt(8)
	v_fma_f32 v162, v179, v82, 0
	ds_read_b128 v[86:89], v137 offset:18432
	ds_read_b128 v[90:93], v137 offset:19456
	s_waitcnt lgkmcnt(4)
	v_fma_f32 v163, v179, v94, 0
	v_fmac_f32_e32 v158, v200, v103
	v_fmac_f32_e32 v162, v200, v83
	v_fmac_f32_e32 v163, v200, v95
	v_fma_f32 v151, v179, v74, 0
	v_fma_f32 v152, v179, v78, 0
	v_fmac_f32_e32 v158, v201, v104
	v_fmac_f32_e32 v162, v201, v84
	v_fmac_f32_e32 v163, v201, v96
	v_fmac_f32_e32 v151, v200, v75
	v_fmac_f32_e32 v152, v200, v79
	v_fmac_f32_e32 v158, v202, v105
	v_fmac_f32_e32 v162, v202, v85
	v_fmac_f32_e32 v163, v202, v97
	ds_read_b128 v[82:85], v137 offset:20496
	s_waitcnt lgkmcnt(3)
	v_fma_f32 v166, v179, v98, 0
	ds_read_b128 v[94:97], v137 offset:21504
	ds_read_b128 v[102:105], v137 offset:22528
	v_fmac_f32_e32 v151, v201, v76
	v_fmac_f32_e32 v152, v201, v80
	v_fmac_f32_e32 v166, v200, v99
	v_fmac_f32_e32 v151, v202, v77
	v_fmac_f32_e32 v152, v202, v81
	ds_read_b128 v[74:77], v137 offset:18448
	s_waitcnt lgkmcnt(5)
	v_fma_f32 v164, v179, v86, 0
	ds_read_b128 v[78:81], v137 offset:19472
	s_waitcnt lgkmcnt(5)
	v_fma_f32 v165, v179, v90, 0
	v_fmac_f32_e32 v166, v201, v100
	v_fmac_f32_e32 v164, v200, v87
	v_fmac_f32_e32 v165, v200, v91
	v_fmac_f32_e32 v166, v202, v101
	ds_read_b128 v[98:101], v137 offset:23552
	v_fmac_f32_e32 v164, v201, v88
	v_fmac_f32_e32 v165, v201, v92
	v_fmac_f32_e32 v164, v202, v89
	v_fmac_f32_e32 v165, v202, v93
	ds_read_b128 v[86:89], v137 offset:21520
	s_waitcnt lgkmcnt(5)
	v_fma_f32 v167, v179, v94, 0
	ds_read_b128 v[90:93], v137 offset:22544
	s_waitcnt lgkmcnt(5)
	v_fma_f32 v168, v179, v102, 0
	v_fmac_f32_e32 v167, v200, v95
	v_fmac_f32_e32 v168, v200, v103
	v_fmac_f32_e32 v167, v201, v96
	v_fmac_f32_e32 v168, v201, v104
	v_fma_f32 v159, v179, v106, 0
	v_fmac_f32_e32 v167, v202, v97
	v_fmac_f32_e32 v168, v202, v105
	ds_read_b128 v[102:105], v137 offset:24576
	ds_read_b128 v[94:97], v137 offset:23568
	s_waitcnt lgkmcnt(4)
	v_fma_f32 v169, v179, v98, 0
	v_fmac_f32_e32 v159, v200, v107
	v_fmac_f32_e32 v169, v200, v99
	v_fmac_f32_e32 v159, v201, v108
	v_fmac_f32_e32 v169, v201, v100
	v_fmac_f32_e32 v159, v202, v109
	v_fmac_f32_e32 v169, v202, v101
	ds_read_b128 v[98:101], v137 offset:24592
	ds_read_b128 v[106:109], v137 offset:25600
	v_fma_f32 v160, v179, v110, 0
	s_waitcnt lgkmcnt(3)
	v_fma_f32 v170, v179, v102, 0
	v_fmac_f32_e32 v160, v200, v111
	v_fmac_f32_e32 v170, v200, v103
	v_fmac_f32_e32 v160, v201, v112
	v_fmac_f32_e32 v170, v201, v104
	v_fmac_f32_e32 v160, v202, v113
	v_fmac_f32_e32 v170, v202, v105
	ds_read_b128 v[110:113], v137 offset:26624
	ds_read_b128 v[102:105], v137 offset:25616
	v_fma_f32 v161, v179, v114, 0
	s_waitcnt lgkmcnt(2)
	v_fma_f32 v171, v179, v106, 0
	v_fmac_f32_e32 v161, v200, v115
	v_fmac_f32_e32 v171, v200, v107
	v_fmac_f32_e32 v161, v201, v116
	v_fmac_f32_e32 v171, v201, v108
	v_fmac_f32_e32 v161, v202, v117
	v_fmac_f32_e32 v171, v202, v109
	ds_read_b128 v[106:109], v137 offset:26640
	ds_read_b128 v[114:117], v137 offset:27648
	s_waitcnt lgkmcnt(3)
	v_fma_f32 v172, v179, v110, 0
	v_fmac_f32_e32 v172, v200, v111
	v_fmac_f32_e32 v172, v201, v112
	v_fmac_f32_e32 v172, v202, v113
	ds_read_b128 v[118:121], v137 offset:28672
	ds_read_b128 v[110:113], v137 offset:27664
	s_waitcnt lgkmcnt(2)
	v_fma_f32 v173, v179, v114, 0
	v_fmac_f32_e32 v173, v200, v115
	v_fmac_f32_e32 v173, v201, v116
	s_waitcnt lgkmcnt(1)
	v_fma_f32 v174, v179, v118, 0
	v_fmac_f32_e32 v173, v202, v117
	ds_read_b128 v[114:117], v137 offset:28688
	ds_read_b128 v[122:125], v137 offset:29696
	v_fmac_f32_e32 v174, v200, v119
	v_fmac_f32_e32 v174, v201, v120
	v_fmac_f32_e32 v174, v202, v121
	ds_read_b128 v[204:207], v137 offset:30720
	ds_read_b128 v[118:121], v137 offset:29712
	s_waitcnt lgkmcnt(2)
	v_fma_f32 v175, v179, v122, 0
	v_fmac_f32_e32 v175, v200, v123
	v_fmac_f32_e32 v175, v201, v124
	s_waitcnt lgkmcnt(1)
	v_fma_f32 v176, v179, v204, 0
	v_fmac_f32_e32 v176, v200, v205
	v_fmac_f32_e32 v175, v202, v125
	ds_read_b128 v[122:125], v137 offset:30736
	ds_read_b128 v[208:211], v137 offset:31744
	v_fmac_f32_e32 v176, v201, v206
	v_fmac_f32_e32 v176, v202, v207
	ds_read_b128 v[204:207], v137 offset:32768
	ds_read_b128 v[212:215], v137 offset:31760
	v_fmac_f32_e32 v139, v199, v2
	s_waitcnt lgkmcnt(2)
	v_fma_f32 v177, v179, v208, 0
	v_fmac_f32_e32 v147, v199, v26
	s_waitcnt lgkmcnt(1)
	v_fma_f32 v178, v179, v204, 0
	v_fmac_f32_e32 v148, v199, v30
	v_fmac_f32_e32 v149, v199, v34
	v_fmac_f32_e32 v150, v199, v38
	v_fmac_f32_e32 v151, v199, v42
	v_fmac_f32_e32 v152, v199, v46
	v_fmac_f32_e32 v153, v199, v50
	v_fmac_f32_e32 v157, v199, v66
	v_fmac_f32_e32 v158, v199, v70
	v_fmac_f32_e32 v159, v199, v6
	v_fmac_f32_e32 v160, v199, v14
	v_fmac_f32_e32 v161, v199, v10
	v_fmac_f32_e32 v162, v199, v18
	v_fmac_f32_e32 v163, v199, v22
	v_fmac_f32_e32 v164, v199, v74
	v_fmac_f32_e32 v165, v199, v78
	v_fmac_f32_e32 v177, v200, v209
	v_fmac_f32_e32 v178, v200, v205
	v_fmac_f32_e32 v139, v198, v3
	v_fmac_f32_e32 v147, v198, v27
	v_fmac_f32_e32 v148, v198, v31
	v_fmac_f32_e32 v149, v198, v35
	v_fmac_f32_e32 v150, v198, v39
	v_fmac_f32_e32 v151, v198, v43
	v_fmac_f32_e32 v152, v198, v47
	v_fmac_f32_e32 v153, v198, v51
	v_fmac_f32_e32 v157, v198, v67
	v_fmac_f32_e32 v158, v198, v71
	v_fmac_f32_e32 v159, v198, v7
	v_fmac_f32_e32 v160, v198, v15
	v_fmac_f32_e32 v161, v198, v11
	v_fmac_f32_e32 v162, v198, v19
	v_fmac_f32_e32 v163, v198, v23
	v_fmac_f32_e32 v164, v198, v75
	v_fmac_f32_e32 v165, v198, v79
	v_fmac_f32_e32 v177, v201, v210
	v_fmac_f32_e32 v178, v201, v206
	v_fmac_f32_e32 v139, v197, v4
	v_fmac_f32_e32 v147, v197, v28
	v_fmac_f32_e32 v148, v197, v32
	v_fmac_f32_e32 v149, v197, v36
	v_fmac_f32_e32 v150, v197, v40
	v_fmac_f32_e32 v151, v197, v44
	v_fmac_f32_e32 v152, v197, v48
	v_fmac_f32_e32 v153, v197, v52
	v_fmac_f32_e32 v154, v199, v54
	v_fmac_f32_e32 v157, v197, v68
	v_fmac_f32_e32 v158, v197, v72
	v_fmac_f32_e32 v166, v199, v82
	v_fmac_f32_e32 v167, v199, v86
	v_fmac_f32_e32 v168, v199, v90
	v_fmac_f32_e32 v159, v197, v8
	v_fmac_f32_e32 v160, v197, v16
	v_fmac_f32_e32 v161, v197, v12
	v_fmac_f32_e32 v162, v197, v20
	v_fmac_f32_e32 v163, v197, v24
	v_fmac_f32_e32 v164, v197, v76
	v_fmac_f32_e32 v165, v197, v80
	v_fmac_f32_e32 v177, v202, v211
	ds_read_b128 v[208:211], v137 offset:32784
	ds_read_b128 v[216:219], v137 offset:33792
	v_fmac_f32_e32 v178, v202, v207
	ds_read_b128 v[204:207], v137 offset:33808
	v_fmac_f32_e32 v139, v196, v5
	v_fmac_f32_e32 v147, v196, v29
	v_fmac_f32_e32 v148, v196, v33
	v_fmac_f32_e32 v149, v196, v37
	v_fmac_f32_e32 v150, v196, v41
	v_fmac_f32_e32 v151, v196, v45
	v_fmac_f32_e32 v152, v196, v49
	v_fmac_f32_e32 v153, v196, v53
	v_fmac_f32_e32 v154, v198, v55
	v_fmac_f32_e32 v157, v196, v69
	v_fmac_f32_e32 v158, v196, v73
	v_fmac_f32_e32 v166, v198, v83
	v_fmac_f32_e32 v167, v198, v87
	v_fmac_f32_e32 v168, v198, v91
	v_fmac_f32_e32 v159, v196, v9
	v_fmac_f32_e32 v160, v196, v17
	ds_read_b128 v[6:9], v137 offset:32
	ds_read_b128 v[2:5], v137 offset:48
	v_fmac_f32_e32 v161, v196, v13
	v_fmac_f32_e32 v162, v196, v21
	v_fmac_f32_e32 v163, v196, v25
	v_fmac_f32_e32 v164, v196, v77
	v_fmac_f32_e32 v165, v196, v81
	ds_read_b128 v[10:13], v137 offset:1056
	ds_read_b128 v[14:17], v137 offset:2080
	ds_read_b128 v[22:25], v137 offset:1072
	ds_read_b128 v[18:21], v137 offset:3104
	ds_read_b128 v[26:29], v137 offset:2096
	ds_read_b128 v[46:49], v137 offset:4128
	ds_read_b128 v[30:33], v137 offset:3120
	ds_read_b128 v[66:69], v137 offset:5152
	ds_read_b128 v[34:37], v137 offset:4144
	ds_read_b128 v[70:73], v137 offset:6176
	ds_read_b128 v[38:41], v137 offset:5168
	ds_read_b128 v[74:77], v137 offset:7200
	ds_read_b128 v[42:45], v137 offset:6192
	ds_read_b128 v[78:81], v137 offset:8224
	ds_read_b128 v[50:53], v137 offset:7216
	v_fmac_f32_e32 v154, v197, v56
	v_fmac_f32_e32 v166, v197, v84
	v_fmac_f32_e32 v167, v197, v88
	v_fmac_f32_e32 v168, v197, v92
	v_fmac_f32_e32 v154, v196, v57
	v_fmac_f32_e32 v166, v196, v85
	v_fmac_f32_e32 v167, v196, v89
	v_fmac_f32_e32 v168, v196, v93
	ds_read_b128 v[82:85], v137 offset:9248
	ds_read_b128 v[86:89], v137 offset:10272
	ds_read_b128 v[54:57], v137 offset:8240
	ds_read_b128 v[90:93], v137 offset:11296
	s_waitcnt lgkmcnt(14)
	v_fmac_f32_e32 v139, v192, v6
	s_waitcnt lgkmcnt(5)
	v_fmac_f32_e32 v154, v192, v78
	v_fmac_f32_e32 v169, v199, v94
	v_fmac_f32_e32 v139, v193, v7
	v_fmac_f32_e32 v154, v193, v79
	v_fmac_f32_e32 v155, v199, v58
	v_fmac_f32_e32 v169, v198, v95
	v_fmac_f32_e32 v139, v194, v8
	v_fmac_f32_e32 v154, v194, v80
	v_fmac_f32_e32 v155, v198, v59
	v_fmac_f32_e32 v169, v197, v96
	v_fmac_f32_e32 v152, v192, v70
	v_fmac_f32_e32 v139, v195, v9
	ds_read_b128 v[6:9], v137 offset:11312
	s_waitcnt lgkmcnt(1)
	v_fmac_f32_e32 v157, v192, v90
	v_fmac_f32_e32 v154, v195, v81
	ds_read_b128 v[78:81], v137 offset:16416
	v_fmac_f32_e32 v155, v197, v60
	v_fmac_f32_e32 v169, v196, v97
	ds_read_b128 v[94:97], v137 offset:12320
	v_fmac_f32_e32 v152, v193, v71
	v_fmac_f32_e32 v157, v193, v91
	v_fmac_f32_e32 v155, v196, v61
	v_fmac_f32_e32 v156, v199, v62
	v_fmac_f32_e32 v151, v192, v66
	v_fmac_f32_e32 v152, v194, v72
	v_fmac_f32_e32 v157, v194, v92
	v_fmac_f32_e32 v156, v198, v63
	v_fmac_f32_e32 v147, v192, v10
	v_fmac_f32_e32 v153, v192, v74
	v_fmac_f32_e32 v155, v192, v82
	v_fmac_f32_e32 v151, v193, v67
	v_fmac_f32_e32 v152, v195, v73
	ds_read_b128 v[70:73], v137 offset:14368
	v_fmac_f32_e32 v157, v195, v93
	ds_read_b128 v[90:93], v137 offset:19488
	v_fmac_f32_e32 v156, v197, v64
	v_fmac_f32_e32 v147, v193, v11
	v_fmac_f32_e32 v151, v194, v68
	v_fmac_f32_e32 v153, v193, v75
	v_fmac_f32_e32 v155, v193, v83
	v_fmac_f32_e32 v156, v196, v65
	v_fmac_f32_e32 v149, v192, v18
	v_fmac_f32_e32 v147, v194, v12
	v_fmac_f32_e32 v151, v195, v69
	v_fmac_f32_e32 v153, v194, v76
	v_fmac_f32_e32 v155, v194, v84
	ds_read_b128 v[66:69], v137 offset:16432
	s_waitcnt lgkmcnt(4)
	v_fmac_f32_e32 v162, v192, v78
	v_fmac_f32_e32 v156, v192, v86
	v_fmac_f32_e32 v147, v195, v13
	v_fmac_f32_e32 v149, v193, v19
	ds_read_b128 v[10:13], v137 offset:12336
	s_waitcnt lgkmcnt(4)
	v_fmac_f32_e32 v158, v192, v94
	v_fmac_f32_e32 v153, v195, v77
	v_fmac_f32_e32 v155, v195, v85
	ds_read_b128 v[74:77], v137 offset:15392
	ds_read_b128 v[82:85], v137 offset:17440
	v_fmac_f32_e32 v162, v193, v79
	v_fmac_f32_e32 v149, v194, v20
	v_fmac_f32_e32 v156, v193, v87
	v_fmac_f32_e32 v158, v193, v95
	v_fmac_f32_e32 v162, v194, v80
	v_fmac_f32_e32 v170, v199, v98
	v_fmac_f32_e32 v150, v192, v46
	v_fmac_f32_e32 v149, v195, v21
	ds_read_b128 v[18:21], v137 offset:14384
	s_waitcnt lgkmcnt(6)
	v_fmac_f32_e32 v160, v192, v70
	v_fmac_f32_e32 v156, v194, v88
	v_fmac_f32_e32 v158, v194, v96
	v_fmac_f32_e32 v162, v195, v81
	ds_read_b128 v[78:81], v137 offset:19504
	s_waitcnt lgkmcnt(6)
	v_fmac_f32_e32 v165, v192, v90
	v_fmac_f32_e32 v170, v198, v99
	v_fmac_f32_e32 v150, v193, v47
	v_fmac_f32_e32 v156, v195, v89
	v_fmac_f32_e32 v158, v195, v97
	v_fmac_f32_e32 v160, v193, v71
	ds_read_b128 v[86:89], v137 offset:18464
	ds_read_b128 v[94:97], v137 offset:20512
	v_fmac_f32_e32 v165, v193, v91
	v_fmac_f32_e32 v170, v197, v100
	v_fmac_f32_e32 v150, v194, v48
	v_fmac_f32_e32 v160, v194, v72
	v_fmac_f32_e32 v165, v194, v92
	v_fmac_f32_e32 v170, v196, v101
	v_fmac_f32_e32 v150, v195, v49
	ds_read_b128 v[98:101], v137 offset:13344
	ds_read_b128 v[46:49], v137 offset:15408
	s_waitcnt lgkmcnt(7)
	v_fmac_f32_e32 v161, v192, v74
	v_fmac_f32_e32 v160, v195, v73
	ds_read_b128 v[70:73], v137 offset:17456
	s_waitcnt lgkmcnt(7)
	v_fmac_f32_e32 v163, v192, v82
	v_fmac_f32_e32 v165, v195, v93
	ds_read_b128 v[90:93], v137 offset:21536
	v_fmac_f32_e32 v161, v193, v75
	v_fmac_f32_e32 v163, v193, v83
	v_fmac_f32_e32 v148, v192, v14
	v_fmac_f32_e32 v161, v194, v76
	v_fmac_f32_e32 v163, v194, v84
	v_fmac_f32_e32 v148, v193, v15
	v_fmac_f32_e32 v161, v195, v77
	ds_read_b128 v[74:77], v137 offset:18480
	s_waitcnt lgkmcnt(6)
	v_fmac_f32_e32 v164, v192, v86
	v_fmac_f32_e32 v163, v195, v85
	ds_read_b128 v[82:85], v137 offset:20528
	s_waitcnt lgkmcnt(6)
	v_fmac_f32_e32 v166, v192, v94
	v_fmac_f32_e32 v148, v194, v16
	v_fmac_f32_e32 v164, v193, v87
	v_fmac_f32_e32 v166, v193, v95
	v_fmac_f32_e32 v148, v195, v17
	ds_read_b128 v[14:17], v137 offset:13360
	s_waitcnt lgkmcnt(6)
	v_fmac_f32_e32 v159, v192, v98
	v_fmac_f32_e32 v164, v194, v88
	v_fmac_f32_e32 v166, v194, v96
	s_waitcnt lgkmcnt(3)
	v_fmac_f32_e32 v167, v192, v90
	ds_read_b128 v[58:61], v137 offset:9264
	ds_read_b128 v[62:65], v137 offset:10288
	v_fmac_f32_e32 v159, v193, v99
	v_fmac_f32_e32 v164, v195, v89
	v_fmac_f32_e32 v166, v195, v97
	ds_read_b128 v[94:97], v137 offset:22560
	ds_read_b128 v[86:89], v137 offset:21552
	v_fmac_f32_e32 v167, v193, v91
	v_fmac_f32_e32 v159, v194, v100
	v_fmac_f32_e32 v167, v194, v92
	v_fmac_f32_e32 v159, v195, v101
	v_fmac_f32_e32 v167, v195, v93
	ds_read_b128 v[90:93], v137 offset:22576
	ds_read_b128 v[98:101], v137 offset:23584
	v_fmac_f32_e32 v171, v199, v102
	s_waitcnt lgkmcnt(3)
	v_fmac_f32_e32 v168, v192, v94
	v_fmac_f32_e32 v171, v198, v103
	v_fmac_f32_e32 v168, v193, v95
	v_fmac_f32_e32 v171, v197, v104
	v_fmac_f32_e32 v168, v194, v96
	v_fmac_f32_e32 v172, v199, v106
	v_fmac_f32_e32 v171, v196, v105
	v_fmac_f32_e32 v168, v195, v97
	ds_read_b128 v[102:105], v137 offset:24608
	ds_read_b128 v[94:97], v137 offset:23600
	s_waitcnt lgkmcnt(2)
	v_fmac_f32_e32 v169, v192, v98
	v_fmac_f32_e32 v172, v198, v107
	v_fmac_f32_e32 v169, v193, v99
	v_fmac_f32_e32 v172, v197, v108
	v_fmac_f32_e32 v169, v194, v100
	v_fmac_f32_e32 v172, v196, v109
	v_fmac_f32_e32 v169, v195, v101
	ds_read_b128 v[98:101], v137 offset:24624
	ds_read_b128 v[106:109], v137 offset:25632
	v_fmac_f32_e32 v173, v199, v110
	s_waitcnt lgkmcnt(3)
	v_fmac_f32_e32 v170, v192, v102
	v_fmac_f32_e32 v173, v198, v111
	v_fmac_f32_e32 v170, v193, v103
	v_fmac_f32_e32 v173, v197, v112
	v_fmac_f32_e32 v170, v194, v104
	v_fmac_f32_e32 v173, v196, v113
	v_fmac_f32_e32 v170, v195, v105
	ds_read_b128 v[110:113], v137 offset:26656
	ds_read_b128 v[102:105], v137 offset:25648
	v_fmac_f32_e32 v174, v199, v114
	s_waitcnt lgkmcnt(2)
	v_fmac_f32_e32 v171, v192, v106
	v_fmac_f32_e32 v174, v198, v115
	v_fmac_f32_e32 v171, v193, v107
	v_fmac_f32_e32 v174, v197, v116
	v_fmac_f32_e32 v171, v194, v108
	v_fmac_f32_e32 v175, v199, v118
	v_fmac_f32_e32 v174, v196, v117
	v_fmac_f32_e32 v171, v195, v109
	ds_read_b128 v[106:109], v137 offset:26672
	ds_read_b128 v[114:117], v137 offset:27680
	s_waitcnt lgkmcnt(3)
	v_fmac_f32_e32 v172, v192, v110
	v_fmac_f32_e32 v175, v198, v119
	v_fmac_f32_e32 v172, v193, v111
	v_fmac_f32_e32 v175, v197, v120
	v_fmac_f32_e32 v172, v194, v112
	v_fma_f32 v179, v179, v216, 0
	v_fmac_f32_e32 v175, v196, v121
	v_fmac_f32_e32 v172, v195, v113
	ds_read_b128 v[118:121], v137 offset:28704
	ds_read_b128 v[110:113], v137 offset:27696
	v_fmac_f32_e32 v179, v200, v217
	v_fmac_f32_e32 v179, v201, v218
	v_fmac_f32_e32 v176, v199, v122
	s_waitcnt lgkmcnt(2)
	v_fmac_f32_e32 v173, v192, v114
	v_fmac_f32_e32 v179, v202, v219
	v_fmac_f32_e32 v176, v198, v123
	v_fmac_f32_e32 v173, v193, v115
	v_fmac_f32_e32 v177, v199, v212
	v_fmac_f32_e32 v178, v199, v208
	v_fmac_f32_e32 v179, v199, v204
	v_fmac_f32_e32 v176, v197, v124
	v_fmac_f32_e32 v173, v194, v116
	s_waitcnt lgkmcnt(1)
	v_fmac_f32_e32 v174, v192, v118
	v_fmac_f32_e32 v177, v198, v213
	v_fmac_f32_e32 v178, v198, v209
	v_fmac_f32_e32 v179, v198, v205
	v_fmac_f32_e32 v176, v196, v125
	v_fmac_f32_e32 v173, v195, v117
	ds_read_b128 v[114:117], v137 offset:28720
	ds_read_b128 v[122:125], v137 offset:29728
	v_fmac_f32_e32 v174, v193, v119
	v_fmac_f32_e32 v177, v197, v214
	v_fmac_f32_e32 v178, v197, v210
	v_fmac_f32_e32 v179, v197, v206
	v_fmac_f32_e32 v174, v194, v120
	v_fmac_f32_e32 v177, v196, v215
	v_fmac_f32_e32 v178, v196, v211
	v_fmac_f32_e32 v179, v196, v207
	v_fmac_f32_e32 v174, v195, v121
	ds_read_b128 v[196:199], v137 offset:30752
	ds_read_b128 v[118:121], v137 offset:29744
	s_waitcnt lgkmcnt(2)
	v_fmac_f32_e32 v175, v192, v122
	v_fmac_f32_e32 v175, v193, v123
	v_fmac_f32_e32 v175, v194, v124
	s_waitcnt lgkmcnt(1)
	v_fmac_f32_e32 v176, v192, v196
	v_fmac_f32_e32 v176, v193, v197
	v_fmac_f32_e32 v175, v195, v125
	ds_read_b128 v[122:125], v137 offset:30768
	ds_read_b128 v[200:203], v137 offset:31776
	v_fmac_f32_e32 v176, v194, v198
	v_fmac_f32_e32 v176, v195, v199
	ds_read_b128 v[196:199], v137 offset:32800
	ds_read_b128 v[204:207], v137 offset:31792
	v_fmac_f32_e32 v149, v191, v30
	s_waitcnt lgkmcnt(2)
	v_fmac_f32_e32 v177, v192, v200
	v_fmac_f32_e32 v150, v191, v34
	s_waitcnt lgkmcnt(1)
	v_fmac_f32_e32 v178, v192, v196
	v_fmac_f32_e32 v158, v191, v10
	v_fmac_f32_e32 v159, v191, v14
	v_fmac_f32_e32 v160, v191, v18
	v_fmac_f32_e32 v177, v193, v201
	v_fmac_f32_e32 v178, v193, v197
	v_fmac_f32_e32 v139, v191, v2
	v_fmac_f32_e32 v147, v191, v22
	v_fmac_f32_e32 v148, v191, v26
	v_fmac_f32_e32 v149, v190, v31
	v_fmac_f32_e32 v150, v190, v35
	v_fmac_f32_e32 v151, v191, v38
	v_fmac_f32_e32 v152, v191, v42
	v_fmac_f32_e32 v153, v191, v50
	v_fmac_f32_e32 v154, v191, v54
	v_fmac_f32_e32 v155, v191, v58
	v_fmac_f32_e32 v156, v191, v62
	v_fmac_f32_e32 v161, v191, v46
	v_fmac_f32_e32 v162, v191, v66
	v_fmac_f32_e32 v163, v191, v70
	v_fmac_f32_e32 v164, v191, v74
	v_fmac_f32_e32 v165, v191, v78
	v_fmac_f32_e32 v166, v191, v82
	v_fmac_f32_e32 v167, v191, v86
	v_fmac_f32_e32 v168, v191, v90
	v_fmac_f32_e32 v158, v190, v11
	v_fmac_f32_e32 v159, v190, v15
	v_fmac_f32_e32 v160, v190, v19
	v_fmac_f32_e32 v177, v194, v202
	v_fmac_f32_e32 v178, v194, v198
	v_fmac_f32_e32 v139, v190, v3
	v_fmac_f32_e32 v147, v190, v23
	v_fmac_f32_e32 v148, v190, v27
	v_fmac_f32_e32 v149, v189, v32
	v_fmac_f32_e32 v150, v189, v36
	v_fmac_f32_e32 v151, v190, v39
	v_fmac_f32_e32 v152, v190, v43
	v_fmac_f32_e32 v153, v190, v51
	v_fmac_f32_e32 v154, v190, v55
	v_fmac_f32_e32 v155, v190, v59
	v_fmac_f32_e32 v156, v190, v63
	v_fmac_f32_e32 v170, v191, v98
	v_fmac_f32_e32 v161, v190, v47
	v_fmac_f32_e32 v162, v190, v67
	v_fmac_f32_e32 v163, v190, v71
	v_fmac_f32_e32 v164, v190, v75
	v_fmac_f32_e32 v165, v190, v79
	v_fmac_f32_e32 v166, v190, v83
	v_fmac_f32_e32 v167, v190, v87
	v_fmac_f32_e32 v168, v190, v91
	v_fmac_f32_e32 v158, v189, v12
	v_fmac_f32_e32 v159, v189, v16
	v_fmac_f32_e32 v160, v189, v20
	v_fmac_f32_e32 v177, v195, v203
	ds_read_b128 v[200:203], v137 offset:32816
	ds_read_b128 v[208:211], v137 offset:33824
	v_fmac_f32_e32 v178, v195, v199
	ds_read_b128 v[196:199], v137 offset:33840
	v_fmac_f32_e32 v139, v189, v4
	v_fmac_f32_e32 v147, v189, v24
	v_fmac_f32_e32 v148, v189, v28
	v_fmac_f32_e32 v149, v188, v33
	v_fmac_f32_e32 v150, v188, v37
	v_fmac_f32_e32 v151, v189, v40
	v_fmac_f32_e32 v152, v189, v44
	v_fmac_f32_e32 v153, v189, v52
	v_fmac_f32_e32 v154, v189, v56
	v_fmac_f32_e32 v155, v189, v60
	v_fmac_f32_e32 v156, v189, v64
	v_fmac_f32_e32 v170, v190, v99
	v_fmac_f32_e32 v161, v189, v48
	v_fmac_f32_e32 v162, v189, v68
	v_fmac_f32_e32 v163, v189, v72
	v_fmac_f32_e32 v164, v189, v76
	v_fmac_f32_e32 v165, v189, v80
	v_fmac_f32_e32 v166, v189, v84
	v_fmac_f32_e32 v167, v189, v88
	v_fmac_f32_e32 v168, v189, v92
	v_fmac_f32_e32 v158, v188, v13
	v_fmac_f32_e32 v159, v188, v17
	v_fmac_f32_e32 v160, v188, v21
	ds_read_b128 v[10:13], v137 offset:64
	ds_read_b128 v[14:17], v137 offset:1088
	ds_read_b128 v[30:33], v137 offset:80
	ds_read_b128 v[18:21], v137 offset:2112
	ds_read_b128 v[34:37], v137 offset:1104
	v_fmac_f32_e32 v139, v188, v5
	v_fmac_f32_e32 v147, v188, v25
	v_fmac_f32_e32 v148, v188, v29
	v_fmac_f32_e32 v151, v188, v41
	v_fmac_f32_e32 v152, v188, v45
	v_fmac_f32_e32 v153, v188, v53
	v_fmac_f32_e32 v154, v188, v57
	v_fmac_f32_e32 v155, v188, v61
	v_fmac_f32_e32 v156, v188, v65
	v_fmac_f32_e32 v170, v189, v100
	v_fmac_f32_e32 v161, v188, v49
	v_fmac_f32_e32 v162, v188, v69
	v_fmac_f32_e32 v163, v188, v73
	v_fmac_f32_e32 v164, v188, v77
	v_fmac_f32_e32 v165, v188, v81
	v_fmac_f32_e32 v166, v188, v85
	v_fmac_f32_e32 v167, v188, v89
	v_fmac_f32_e32 v168, v188, v93
	ds_read_b128 v[22:25], v137 offset:3136
	ds_read_b128 v[38:41], v137 offset:2128
	ds_read_b128 v[26:29], v137 offset:4160
	ds_read_b128 v[42:45], v137 offset:3152
	ds_read_b128 v[62:65], v137 offset:5184
	ds_read_b128 v[46:49], v137 offset:4176
	ds_read_b128 v[70:73], v137 offset:6208
	ds_read_b128 v[50:53], v137 offset:5200
	ds_read_b128 v[74:77], v137 offset:7232
	ds_read_b128 v[54:57], v137 offset:6224
	ds_read_b128 v[78:81], v137 offset:8256
	ds_read_b128 v[58:61], v137 offset:7248
	ds_read_b128 v[82:85], v137 offset:9280
	ds_read_b128 v[66:69], v137 offset:8272
	ds_read_b128 v[86:89], v137 offset:10304
	ds_read_b128 v[90:93], v137 offset:11328
	ds_read_b128 v[2:5], v137 offset:9296
	v_fmac_f32_e32 v170, v188, v101
	ds_read_b128 v[98:101], v137 offset:13376
	v_fmac_f32_e32 v169, v191, v94
	v_fmac_f32_e32 v171, v191, v102
	s_waitcnt lgkmcnt(14)
	v_fmac_f32_e32 v148, v184, v18
	s_waitcnt lgkmcnt(3)
	v_fmac_f32_e32 v156, v184, v86
	v_fmac_f32_e32 v157, v191, v6
	v_fmac_f32_e32 v169, v190, v95
	v_fmac_f32_e32 v171, v190, v103
	v_fmac_f32_e32 v148, v185, v19
	v_fmac_f32_e32 v156, v185, v87
	v_fmac_f32_e32 v157, v190, v7
	v_fmac_f32_e32 v169, v189, v96
	v_fmac_f32_e32 v171, v189, v104
	v_fmac_f32_e32 v154, v184, v78
	v_fmac_f32_e32 v148, v186, v20
	v_fmac_f32_e32 v156, v186, v88
	v_fmac_f32_e32 v157, v189, v8
	v_fmac_f32_e32 v169, v188, v97
	v_fmac_f32_e32 v171, v188, v105
	ds_read_b128 v[94:97], v137 offset:12352
	v_fmac_f32_e32 v148, v187, v21
	ds_read_b128 v[18:21], v137 offset:13392
	s_waitcnt lgkmcnt(2)
	v_fmac_f32_e32 v159, v184, v98
	ds_read_b128 v[102:105], v137 offset:14400
	v_fmac_f32_e32 v154, v185, v79
	v_fmac_f32_e32 v156, v187, v89
	ds_read_b128 v[86:89], v137 offset:18496
	v_fmac_f32_e32 v157, v188, v9
	v_fmac_f32_e32 v154, v186, v80
	v_fmac_f32_e32 v159, v185, v99
	v_fmac_f32_e32 v147, v184, v14
	v_fmac_f32_e32 v149, v184, v22
	v_fmac_f32_e32 v153, v184, v74
	v_fmac_f32_e32 v155, v184, v82
	v_fmac_f32_e32 v157, v184, v90
	v_fmac_f32_e32 v154, v187, v81
	ds_read_b128 v[78:81], v137 offset:16448
	v_fmac_f32_e32 v159, v186, v100
	v_fmac_f32_e32 v147, v185, v15
	v_fmac_f32_e32 v149, v185, v23
	v_fmac_f32_e32 v153, v185, v75
	v_fmac_f32_e32 v155, v185, v83
	v_fmac_f32_e32 v157, v185, v91
	v_fmac_f32_e32 v159, v187, v101
	ds_read_b128 v[98:101], v137 offset:21568
	v_fmac_f32_e32 v151, v184, v62
	v_fmac_f32_e32 v147, v186, v16
	v_fmac_f32_e32 v149, v186, v24
	v_fmac_f32_e32 v153, v186, v76
	v_fmac_f32_e32 v155, v186, v84
	v_fmac_f32_e32 v157, v186, v92
	v_fmac_f32_e32 v147, v187, v17
	ds_read_b128 v[14:17], v137 offset:12368
	s_waitcnt lgkmcnt(6)
	v_fmac_f32_e32 v158, v184, v94
	v_fmac_f32_e32 v149, v187, v25
	v_fmac_f32_e32 v151, v185, v63
	ds_read_b128 v[22:25], v137 offset:14416
	s_waitcnt lgkmcnt(5)
	v_fmac_f32_e32 v160, v184, v102
	v_fmac_f32_e32 v153, v187, v77
	v_fmac_f32_e32 v155, v187, v85
	v_fmac_f32_e32 v157, v187, v93
	ds_read_b128 v[82:85], v137 offset:17472
	ds_read_b128 v[74:77], v137 offset:18512
	s_waitcnt lgkmcnt(6)
	v_fmac_f32_e32 v164, v184, v86
	ds_read_b128 v[90:93], v137 offset:19520
	v_fmac_f32_e32 v151, v186, v64
	v_fmac_f32_e32 v158, v185, v95
	v_fmac_f32_e32 v160, v185, v103
	v_fmac_f32_e32 v164, v185, v87
	v_fmac_f32_e32 v152, v184, v70
	v_fmac_f32_e32 v151, v187, v65
	ds_read_b128 v[62:65], v137 offset:16464
	s_waitcnt lgkmcnt(7)
	v_fmac_f32_e32 v162, v184, v78
	v_fmac_f32_e32 v158, v186, v96
	v_fmac_f32_e32 v160, v186, v104
	v_fmac_f32_e32 v164, v186, v88
	v_fmac_f32_e32 v172, v191, v106
	v_fmac_f32_e32 v152, v185, v71
	v_fmac_f32_e32 v158, v187, v97
	v_fmac_f32_e32 v160, v187, v105
	v_fmac_f32_e32 v162, v185, v79
	ds_read_b128 v[94:97], v137 offset:20544
	v_fmac_f32_e32 v164, v187, v89
	ds_read_b128 v[102:105], v137 offset:22592
	ds_read_b128 v[86:89], v137 offset:21584
	s_waitcnt lgkmcnt(9)
	v_fmac_f32_e32 v167, v184, v98
	v_fmac_f32_e32 v172, v190, v107
	v_fmac_f32_e32 v152, v186, v72
	v_fmac_f32_e32 v162, v186, v80
	v_fmac_f32_e32 v167, v185, v99
	v_fmac_f32_e32 v172, v189, v108
	v_fmac_f32_e32 v152, v187, v73
	ds_read_b128 v[70:73], v137 offset:17488
	s_waitcnt lgkmcnt(7)
	v_fmac_f32_e32 v163, v184, v82
	v_fmac_f32_e32 v162, v187, v81
	ds_read_b128 v[78:81], v137 offset:19536
	s_waitcnt lgkmcnt(6)
	v_fmac_f32_e32 v165, v184, v90
	v_fmac_f32_e32 v167, v186, v100
	v_fmac_f32_e32 v172, v188, v109
	ds_read_b128 v[106:109], v137 offset:15424
	v_fmac_f32_e32 v163, v185, v83
	v_fmac_f32_e32 v165, v185, v91
	v_fmac_f32_e32 v167, v187, v101
	ds_read_b128 v[98:101], v137 offset:23616
	v_fmac_f32_e32 v163, v186, v84
	v_fmac_f32_e32 v165, v186, v92
	v_fmac_f32_e32 v139, v184, v10
	v_fmac_f32_e32 v150, v184, v26
	v_fmac_f32_e32 v163, v187, v85
	ds_read_b128 v[82:85], v137 offset:20560
	s_waitcnt lgkmcnt(7)
	v_fmac_f32_e32 v166, v184, v94
	v_fmac_f32_e32 v165, v187, v93
	ds_read_b128 v[90:93], v137 offset:22608
	s_waitcnt lgkmcnt(7)
	v_fmac_f32_e32 v168, v184, v102
	v_fmac_f32_e32 v139, v185, v11
	v_fmac_f32_e32 v150, v185, v27
	v_fmac_f32_e32 v166, v185, v95
	v_fmac_f32_e32 v168, v185, v103
	v_fmac_f32_e32 v139, v186, v12
	v_fmac_f32_e32 v150, v186, v28
	v_fmac_f32_e32 v166, v186, v96
	v_fmac_f32_e32 v168, v186, v104
	ds_read_b128 v[6:9], v137 offset:10320
	v_fmac_f32_e32 v139, v187, v13
	ds_read_b128 v[10:13], v137 offset:11344
	v_fmac_f32_e32 v150, v187, v29
	ds_read_b128 v[26:29], v137 offset:15440
	s_waitcnt lgkmcnt(6)
	v_fmac_f32_e32 v161, v184, v106
	v_fmac_f32_e32 v166, v187, v97
	v_fmac_f32_e32 v168, v187, v105
	ds_read_b128 v[102:105], v137 offset:24640
	ds_read_b128 v[94:97], v137 offset:23632
	s_waitcnt lgkmcnt(7)
	v_fmac_f32_e32 v169, v184, v98
	v_fmac_f32_e32 v161, v185, v107
	v_fmac_f32_e32 v169, v185, v99
	v_fmac_f32_e32 v161, v186, v108
	v_fmac_f32_e32 v169, v186, v100
	v_fmac_f32_e32 v161, v187, v109
	v_fmac_f32_e32 v169, v187, v101
	ds_read_b128 v[98:101], v137 offset:24656
	ds_read_b128 v[106:109], v137 offset:25664
	v_fmac_f32_e32 v173, v191, v110
	s_waitcnt lgkmcnt(3)
	v_fmac_f32_e32 v170, v184, v102
	v_fmac_f32_e32 v173, v190, v111
	v_fmac_f32_e32 v170, v185, v103
	v_fmac_f32_e32 v173, v189, v112
	v_fmac_f32_e32 v170, v186, v104
	v_fmac_f32_e32 v173, v188, v113
	v_fmac_f32_e32 v170, v187, v105
	ds_read_b128 v[110:113], v137 offset:26688
	ds_read_b128 v[102:105], v137 offset:25680
	v_fmac_f32_e32 v174, v191, v114
	s_waitcnt lgkmcnt(2)
	v_fmac_f32_e32 v171, v184, v106
	v_fmac_f32_e32 v174, v190, v115
	v_fmac_f32_e32 v171, v185, v107
	v_fmac_f32_e32 v174, v189, v116
	v_fmac_f32_e32 v171, v186, v108
	v_fmac_f32_e32 v175, v191, v118
	v_fmac_f32_e32 v174, v188, v117
	v_fmac_f32_e32 v171, v187, v109
	ds_read_b128 v[106:109], v137 offset:26704
	ds_read_b128 v[114:117], v137 offset:27712
	s_waitcnt lgkmcnt(3)
	v_fmac_f32_e32 v172, v184, v110
	v_fmac_f32_e32 v175, v190, v119
	v_fmac_f32_e32 v172, v185, v111
	v_fmac_f32_e32 v175, v189, v120
	v_fmac_f32_e32 v172, v186, v112
	v_fmac_f32_e32 v179, v192, v208
	v_fmac_f32_e32 v175, v188, v121
	v_fmac_f32_e32 v172, v187, v113
	ds_read_b128 v[118:121], v137 offset:28736
	ds_read_b128 v[110:113], v137 offset:27728
	v_fmac_f32_e32 v179, v193, v209
	v_fmac_f32_e32 v179, v194, v210
	v_fmac_f32_e32 v176, v191, v122
	s_waitcnt lgkmcnt(2)
	v_fmac_f32_e32 v173, v184, v114
	v_fmac_f32_e32 v179, v195, v211
	v_fmac_f32_e32 v176, v190, v123
	v_fmac_f32_e32 v173, v185, v115
	v_fmac_f32_e32 v177, v191, v204
	v_fmac_f32_e32 v178, v191, v200
	v_fmac_f32_e32 v179, v191, v196
	v_fmac_f32_e32 v176, v189, v124
	v_fmac_f32_e32 v173, v186, v116
	s_waitcnt lgkmcnt(1)
	v_fmac_f32_e32 v174, v184, v118
	v_fmac_f32_e32 v177, v190, v205
	v_fmac_f32_e32 v178, v190, v201
	v_fmac_f32_e32 v179, v190, v197
	v_fmac_f32_e32 v176, v188, v125
	v_fmac_f32_e32 v173, v187, v117
	ds_read_b128 v[114:117], v137 offset:28752
	ds_read_b128 v[122:125], v137 offset:29760
	v_fmac_f32_e32 v174, v185, v119
	v_fmac_f32_e32 v177, v189, v206
	v_fmac_f32_e32 v178, v189, v202
	v_fmac_f32_e32 v179, v189, v198
	v_fmac_f32_e32 v174, v186, v120
	v_fmac_f32_e32 v177, v188, v207
	v_fmac_f32_e32 v178, v188, v203
	v_fmac_f32_e32 v179, v188, v199
	v_fmac_f32_e32 v174, v187, v121
	ds_read_b128 v[188:191], v137 offset:30784
	ds_read_b128 v[118:121], v137 offset:29776
	s_waitcnt lgkmcnt(2)
	v_fmac_f32_e32 v175, v184, v122
	v_fmac_f32_e32 v175, v185, v123
	v_fmac_f32_e32 v175, v186, v124
	s_waitcnt lgkmcnt(1)
	v_fmac_f32_e32 v176, v184, v188
	v_fmac_f32_e32 v176, v185, v189
	v_fmac_f32_e32 v175, v187, v125
	ds_read_b128 v[122:125], v137 offset:30800
	ds_read_b128 v[192:195], v137 offset:31808
	v_fmac_f32_e32 v176, v186, v190
	v_fmac_f32_e32 v176, v187, v191
	ds_read_b128 v[188:191], v137 offset:32832
	ds_read_b128 v[196:199], v137 offset:31824
	v_fmac_f32_e32 v139, v183, v30
	s_waitcnt lgkmcnt(2)
	v_fmac_f32_e32 v177, v184, v192
	v_fmac_f32_e32 v147, v183, v34
	s_waitcnt lgkmcnt(1)
	v_fmac_f32_e32 v178, v184, v188
	v_fmac_f32_e32 v148, v183, v38
	v_fmac_f32_e32 v149, v183, v42
	v_fmac_f32_e32 v150, v183, v46
	v_fmac_f32_e32 v151, v183, v50
	v_fmac_f32_e32 v152, v183, v54
	v_fmac_f32_e32 v153, v183, v58
	v_fmac_f32_e32 v154, v183, v66
	v_fmac_f32_e32 v155, v183, v2
	v_fmac_f32_e32 v156, v183, v6
	v_fmac_f32_e32 v157, v183, v10
	v_fmac_f32_e32 v160, v183, v22
	v_fmac_f32_e32 v161, v183, v26
	v_fmac_f32_e32 v162, v183, v62
	v_fmac_f32_e32 v163, v183, v70
	v_fmac_f32_e32 v164, v183, v74
	v_fmac_f32_e32 v165, v183, v78
	v_fmac_f32_e32 v166, v183, v82
	v_fmac_f32_e32 v167, v183, v86
	v_fmac_f32_e32 v168, v183, v90
	v_fmac_f32_e32 v177, v185, v193
	v_fmac_f32_e32 v178, v185, v189
	v_fmac_f32_e32 v139, v182, v31
	v_fmac_f32_e32 v147, v182, v35
	v_fmac_f32_e32 v148, v182, v39
	v_fmac_f32_e32 v149, v182, v43
	v_fmac_f32_e32 v150, v182, v47
	v_fmac_f32_e32 v151, v182, v51
	v_fmac_f32_e32 v152, v182, v55
	v_fmac_f32_e32 v153, v182, v59
	v_fmac_f32_e32 v154, v182, v67
	v_fmac_f32_e32 v155, v182, v3
	v_fmac_f32_e32 v156, v182, v7
	v_fmac_f32_e32 v157, v182, v11
	v_fmac_f32_e32 v160, v182, v23
	v_fmac_f32_e32 v161, v182, v27
	v_fmac_f32_e32 v162, v182, v63
	v_fmac_f32_e32 v163, v182, v71
	v_fmac_f32_e32 v164, v182, v75
	v_fmac_f32_e32 v165, v182, v79
	v_fmac_f32_e32 v166, v182, v83
	v_fmac_f32_e32 v167, v182, v87
	v_fmac_f32_e32 v168, v182, v91
	v_fmac_f32_e32 v177, v186, v194
	v_fmac_f32_e32 v178, v186, v190
	v_fmac_f32_e32 v139, v181, v32
	v_fmac_f32_e32 v147, v181, v36
	v_fmac_f32_e32 v148, v181, v40
	v_fmac_f32_e32 v149, v181, v44
	v_fmac_f32_e32 v150, v181, v48
	v_fmac_f32_e32 v151, v181, v52
	v_fmac_f32_e32 v152, v181, v56
	v_fmac_f32_e32 v153, v181, v60
	v_fmac_f32_e32 v154, v181, v68
	v_fmac_f32_e32 v158, v183, v14
	v_fmac_f32_e32 v169, v183, v94
	v_fmac_f32_e32 v170, v183, v98
	v_fmac_f32_e32 v171, v183, v102
	v_fmac_f32_e32 v172, v183, v106
	v_fmac_f32_e32 v155, v181, v4
	v_fmac_f32_e32 v156, v181, v8
	v_fmac_f32_e32 v157, v181, v12
	v_fmac_f32_e32 v160, v181, v24
	v_fmac_f32_e32 v161, v181, v28
	v_fmac_f32_e32 v162, v181, v64
	v_fmac_f32_e32 v163, v181, v72
	v_fmac_f32_e32 v164, v181, v76
	v_fmac_f32_e32 v165, v181, v80
	v_fmac_f32_e32 v166, v181, v84
	v_fmac_f32_e32 v167, v181, v88
	v_fmac_f32_e32 v168, v181, v92
	v_fmac_f32_e32 v177, v187, v195
	ds_read_b128 v[192:195], v137 offset:32848
	ds_read_b128 v[200:203], v137 offset:33856
	v_fmac_f32_e32 v178, v187, v191
	ds_read_b128 v[188:191], v137 offset:33872
	v_fmac_f32_e32 v139, v180, v33
	v_fmac_f32_e32 v147, v180, v37
	v_fmac_f32_e32 v148, v180, v41
	v_fmac_f32_e32 v149, v180, v45
	v_fmac_f32_e32 v150, v180, v49
	v_fmac_f32_e32 v151, v180, v53
	v_fmac_f32_e32 v152, v180, v57
	v_fmac_f32_e32 v153, v180, v61
	v_fmac_f32_e32 v154, v180, v69
	v_fmac_f32_e32 v158, v182, v15
	v_fmac_f32_e32 v169, v182, v95
	v_fmac_f32_e32 v170, v182, v99
	v_fmac_f32_e32 v171, v182, v103
	v_fmac_f32_e32 v172, v182, v107
	v_fmac_f32_e32 v155, v180, v5
	v_fmac_f32_e32 v156, v180, v9
	v_fmac_f32_e32 v157, v180, v13
	v_fmac_f32_e32 v160, v180, v25
	v_fmac_f32_e32 v161, v180, v29
	v_fmac_f32_e32 v162, v180, v65
	v_fmac_f32_e32 v163, v180, v73
	v_fmac_f32_e32 v164, v180, v77
	v_fmac_f32_e32 v165, v180, v81
	v_fmac_f32_e32 v166, v180, v85
	v_fmac_f32_e32 v167, v180, v89
	v_fmac_f32_e32 v168, v180, v93
	ds_read_b128 v[22:25], v137 offset:96
	ds_read_b128 v[26:29], v137 offset:1120
	ds_read_b128 v[42:45], v137 offset:112
	ds_read_b128 v[30:33], v137 offset:2144
	ds_read_b128 v[46:49], v137 offset:1136
	ds_read_b128 v[34:37], v137 offset:3168
	ds_read_b128 v[50:53], v137 offset:2160
	ds_read_b128 v[38:41], v137 offset:4192
	ds_read_b128 v[54:57], v137 offset:3184
	ds_read_b128 v[70:73], v137 offset:5216
	ds_read_b128 v[58:61], v137 offset:4208
	ds_read_b128 v[74:77], v137 offset:6240
	ds_read_b128 v[62:65], v137 offset:5232
	ds_read_b128 v[78:81], v137 offset:7264
	ds_read_b128 v[66:69], v137 offset:6256
	ds_read_b128 v[82:85], v137 offset:8288
	ds_read_b128 v[2:5], v137 offset:7280
	ds_read_b128 v[86:89], v137 offset:9312
	ds_read_b128 v[6:9], v137 offset:8304
	ds_read_b128 v[90:93], v137 offset:10336
	ds_read_b128 v[10:13], v137 offset:9328
	v_fmac_f32_e32 v158, v181, v16
	v_fmac_f32_e32 v169, v181, v96
	v_fmac_f32_e32 v170, v181, v100
	v_fmac_f32_e32 v171, v181, v104
	v_fmac_f32_e32 v172, v181, v108
	v_fmac_f32_e32 v158, v180, v17
	v_fmac_f32_e32 v169, v180, v97
	v_fmac_f32_e32 v170, v180, v101
	v_fmac_f32_e32 v171, v180, v105
	v_fmac_f32_e32 v172, v180, v109
	ds_read_b128 v[94:97], v137 offset:11360
	ds_read_b128 v[98:101], v137 offset:12384
	ds_read_b128 v[14:17], v137 offset:10352
	ds_read_b128 v[102:105], v137 offset:13408
	ds_read_b128 v[106:109], v137 offset:14432
	v_fmac_f32_e32 v159, v183, v18
	v_fmac_f32_e32 v159, v182, v19
	s_waitcnt lgkmcnt(14)
	v_fmac_f32_e32 v147, v143, v26
	v_fmac_f32_e32 v148, v143, v30
	s_waitcnt lgkmcnt(8)
	v_fmac_f32_e32 v155, v143, v86
	s_waitcnt lgkmcnt(6)
	v_fmac_f32_e32 v156, v143, v90
	v_fmac_f32_e32 v159, v181, v20
	v_fmac_f32_e32 v147, v144, v27
	v_fmac_f32_e32 v148, v144, v31
	v_fmac_f32_e32 v155, v144, v87
	v_fmac_f32_e32 v156, v144, v91
	v_fmac_f32_e32 v159, v180, v21
	v_fmac_f32_e32 v147, v145, v28
	v_fmac_f32_e32 v148, v145, v32
	v_fmac_f32_e32 v155, v145, v88
	v_fmac_f32_e32 v156, v145, v92
	v_fmac_f32_e32 v173, v183, v110
	v_fmac_f32_e32 v147, v146, v29
	v_fmac_f32_e32 v148, v146, v33
	ds_read_b128 v[26:29], v137 offset:13424
	s_waitcnt lgkmcnt(2)
	v_fmac_f32_e32 v159, v143, v102
	ds_read_b128 v[30:33], v137 offset:14448
	s_waitcnt lgkmcnt(2)
	v_fmac_f32_e32 v160, v143, v106
	v_fmac_f32_e32 v155, v146, v89
	ds_read_b128 v[86:89], v137 offset:17504
	v_fmac_f32_e32 v156, v146, v93
	ds_read_b128 v[90:93], v137 offset:18528
	v_fmac_f32_e32 v173, v182, v111
	v_fmac_f32_e32 v159, v144, v103
	v_fmac_f32_e32 v160, v144, v107
	v_fmac_f32_e32 v173, v181, v112
	v_fmac_f32_e32 v151, v143, v70
	v_fmac_f32_e32 v152, v143, v74
	v_fmac_f32_e32 v159, v145, v104
	v_fmac_f32_e32 v160, v145, v108
	v_fmac_f32_e32 v173, v180, v113
	v_fmac_f32_e32 v151, v144, v71
	ds_read_b128 v[110:113], v137 offset:15456
	v_fmac_f32_e32 v152, v144, v75
	v_fmac_f32_e32 v159, v146, v105
	v_fmac_f32_e32 v160, v146, v109
	ds_read_b128 v[102:105], v137 offset:21600
	ds_read_b128 v[106:109], v137 offset:22624
	v_fmac_f32_e32 v151, v145, v72
	v_fmac_f32_e32 v152, v145, v76
	v_fmac_f32_e32 v149, v143, v34
	v_fmac_f32_e32 v157, v143, v94
	v_fmac_f32_e32 v158, v143, v98
	v_fmac_f32_e32 v151, v146, v73
	v_fmac_f32_e32 v152, v146, v77
	ds_read_b128 v[70:73], v137 offset:17520
	s_waitcnt lgkmcnt(5)
	v_fmac_f32_e32 v163, v143, v86
	ds_read_b128 v[74:77], v137 offset:18544
	s_waitcnt lgkmcnt(5)
	v_fmac_f32_e32 v164, v143, v90
	v_fmac_f32_e32 v149, v144, v35
	v_fmac_f32_e32 v157, v144, v95
	v_fmac_f32_e32 v158, v144, v99
	v_fmac_f32_e32 v163, v144, v87
	v_fmac_f32_e32 v164, v144, v91
	v_fmac_f32_e32 v149, v145, v36
	v_fmac_f32_e32 v157, v145, v96
	v_fmac_f32_e32 v158, v145, v100
	v_fmac_f32_e32 v163, v145, v88
	v_fmac_f32_e32 v164, v145, v92
	v_fmac_f32_e32 v174, v183, v114
	v_fmac_f32_e32 v149, v146, v37
	ds_read_b128 v[34:37], v137 offset:15472
	s_waitcnt lgkmcnt(5)
	v_fmac_f32_e32 v161, v143, v110
	v_fmac_f32_e32 v157, v146, v97
	v_fmac_f32_e32 v158, v146, v101
	ds_read_b128 v[94:97], v137 offset:19552
	ds_read_b128 v[98:101], v137 offset:20576
	v_fmac_f32_e32 v163, v146, v89
	v_fmac_f32_e32 v164, v146, v93
	ds_read_b128 v[86:89], v137 offset:21616
	s_waitcnt lgkmcnt(7)
	v_fmac_f32_e32 v167, v143, v102
	ds_read_b128 v[90:93], v137 offset:22640
	s_waitcnt lgkmcnt(7)
	v_fmac_f32_e32 v168, v143, v106
	v_fmac_f32_e32 v174, v182, v115
	v_fmac_f32_e32 v161, v144, v111
	v_fmac_f32_e32 v167, v144, v103
	v_fmac_f32_e32 v168, v144, v107
	v_fmac_f32_e32 v174, v181, v116
	v_fmac_f32_e32 v153, v143, v78
	v_fmac_f32_e32 v154, v143, v82
	v_fmac_f32_e32 v161, v145, v112
	v_fmac_f32_e32 v167, v145, v104
	v_fmac_f32_e32 v168, v145, v108
	v_fmac_f32_e32 v174, v180, v117
	v_fmac_f32_e32 v153, v144, v79
	ds_read_b128 v[114:117], v137 offset:16480
	v_fmac_f32_e32 v154, v144, v83
	v_fmac_f32_e32 v161, v146, v113
	ds_read_b128 v[110:113], v137 offset:23648
	v_fmac_f32_e32 v167, v146, v105
	ds_read_b128 v[102:105], v137 offset:24672
	v_fmac_f32_e32 v168, v146, v109
	ds_read_b128 v[106:109], v137 offset:25696
	v_fmac_f32_e32 v153, v145, v80
	v_fmac_f32_e32 v154, v145, v84
	v_fmac_f32_e32 v150, v143, v38
	v_fmac_f32_e32 v153, v146, v81
	v_fmac_f32_e32 v154, v146, v85
	ds_read_b128 v[78:81], v137 offset:19568
	s_waitcnt lgkmcnt(8)
	v_fmac_f32_e32 v165, v143, v94
	ds_read_b128 v[82:85], v137 offset:20592
	s_waitcnt lgkmcnt(8)
	v_fmac_f32_e32 v166, v143, v98
	v_fmac_f32_e32 v150, v144, v39
	v_fmac_f32_e32 v165, v144, v95
	v_fmac_f32_e32 v166, v144, v99
	v_fmac_f32_e32 v150, v145, v40
	v_fmac_f32_e32 v165, v145, v96
	v_fmac_f32_e32 v166, v145, v100
	v_fmac_f32_e32 v139, v143, v22
	v_fmac_f32_e32 v150, v146, v41
	ds_read_b128 v[38:41], v137 offset:16496
	s_waitcnt lgkmcnt(6)
	v_fmac_f32_e32 v162, v143, v114
	v_fmac_f32_e32 v165, v146, v97
	v_fmac_f32_e32 v166, v146, v101
	ds_read_b128 v[94:97], v137 offset:23664
	s_waitcnt lgkmcnt(6)
	v_fmac_f32_e32 v169, v143, v110
	ds_read_b128 v[98:101], v137 offset:24688
	s_waitcnt lgkmcnt(6)
	v_fmac_f32_e32 v170, v143, v102
	s_waitcnt lgkmcnt(5)
	v_fmac_f32_e32 v171, v143, v106
	v_fmac_f32_e32 v139, v144, v23
	v_fmac_f32_e32 v162, v144, v115
	v_fmac_f32_e32 v169, v144, v111
	v_fmac_f32_e32 v170, v144, v103
	v_fmac_f32_e32 v171, v144, v107
	v_fmac_f32_e32 v139, v145, v24
	v_fmac_f32_e32 v162, v145, v116
	v_fmac_f32_e32 v169, v145, v112
	v_fmac_f32_e32 v170, v145, v104
	v_fmac_f32_e32 v171, v145, v108
	ds_read_b128 v[18:21], v137 offset:11376
	v_fmac_f32_e32 v139, v146, v25
	ds_read_b128 v[22:25], v137 offset:12400
	v_fmac_f32_e32 v162, v146, v117
	v_fmac_f32_e32 v169, v146, v113
	v_fmac_f32_e32 v170, v146, v105
	ds_read_b128 v[110:113], v137 offset:26720
	ds_read_b128 v[102:105], v137 offset:25712
	v_fmac_f32_e32 v171, v146, v109
	ds_read_b128 v[106:109], v137 offset:26736
	ds_read_b128 v[114:117], v137 offset:27744
	v_fmac_f32_e32 v175, v183, v118
	s_waitcnt lgkmcnt(3)
	v_fmac_f32_e32 v172, v143, v110
	v_fmac_f32_e32 v176, v183, v122
	v_fmac_f32_e32 v175, v182, v119
	v_fmac_f32_e32 v172, v144, v111
	s_waitcnt lgkmcnt(0)
	v_fmac_f32_e32 v173, v143, v114
	v_fmac_f32_e32 v176, v182, v123
	v_fmac_f32_e32 v175, v181, v120
	v_fmac_f32_e32 v172, v145, v112
	v_fmac_f32_e32 v173, v144, v115
	v_fmac_f32_e32 v179, v184, v200
	v_fmac_f32_e32 v176, v181, v124
	v_fmac_f32_e32 v175, v180, v121
	v_fmac_f32_e32 v172, v146, v113
	ds_read_b128 v[118:121], v137 offset:28768
	ds_read_b128 v[110:113], v137 offset:27760
	v_fmac_f32_e32 v173, v145, v116
	v_fmac_f32_e32 v179, v185, v201
	v_fmac_f32_e32 v176, v180, v125
	v_fmac_f32_e32 v173, v146, v117
	ds_read_b128 v[114:117], v137 offset:28784
	ds_read_b128 v[122:125], v137 offset:29792
	v_fmac_f32_e32 v179, v186, v202
	v_fmac_f32_e32 v179, v187, v203
	v_fmac_f32_e32 v177, v183, v196
	v_fmac_f32_e32 v178, v183, v192
	v_fmac_f32_e32 v179, v183, v188
	s_waitcnt lgkmcnt(3)
	v_fmac_f32_e32 v174, v143, v118
	v_fmac_f32_e32 v177, v182, v197
	v_fmac_f32_e32 v178, v182, v193
	v_fmac_f32_e32 v179, v182, v189
	v_fmac_f32_e32 v174, v144, v119
	v_fmac_f32_e32 v177, v181, v198
	v_fmac_f32_e32 v178, v181, v194
	v_fmac_f32_e32 v179, v181, v190
	v_fmac_f32_e32 v174, v145, v120
	s_waitcnt lgkmcnt(0)
	v_fmac_f32_e32 v175, v143, v122
	v_fmac_f32_e32 v177, v180, v199
	v_fmac_f32_e32 v178, v180, v195
	v_fmac_f32_e32 v179, v180, v191
	v_fmac_f32_e32 v174, v146, v121
	ds_read_b128 v[180:183], v137 offset:30816
	ds_read_b128 v[118:121], v137 offset:29808
	v_fmac_f32_e32 v175, v144, v123
	v_fmac_f32_e32 v175, v145, v124
	v_fmac_f32_e32 v175, v146, v125
	ds_read_b128 v[122:125], v137 offset:30832
	ds_read_b128 v[184:187], v137 offset:31840
	s_waitcnt lgkmcnt(3)
	v_fmac_f32_e32 v176, v143, v180
	v_fmac_f32_e32 v176, v144, v181
	v_fmac_f32_e32 v176, v145, v182
	v_fmac_f32_e32 v176, v146, v183
	ds_read_b128 v[180:183], v137 offset:32864
	ds_read_b128 v[188:191], v137 offset:31856
	s_waitcnt lgkmcnt(2)
	v_fmac_f32_e32 v177, v143, v184
	v_fmac_f32_e32 v177, v144, v185
	v_fmac_f32_e32 v177, v145, v186
	v_fmac_f32_e32 v177, v146, v187
	ds_read_b128 v[184:187], v137 offset:32880
	ds_read_b128 v[192:195], v137 offset:33888
	s_waitcnt lgkmcnt(3)
	v_fmac_f32_e32 v178, v143, v180
	v_fmac_f32_e32 v178, v144, v181
	v_fmac_f32_e32 v178, v145, v182
	v_fmac_f32_e32 v178, v146, v183
	ds_read_b128 v[180:183], v137 offset:33904
	s_waitcnt lgkmcnt(1)
	v_fmac_f32_e32 v179, v143, v192
	v_fmac_f32_e32 v179, v144, v193
	v_fmac_f32_e32 v179, v145, v194
	v_fmac_f32_e32 v179, v146, v195
	v_fmac_f32_e32 v139, v142, v42
	v_fmac_f32_e32 v147, v142, v46
	v_fmac_f32_e32 v139, v141, v43
	v_fmac_f32_e32 v147, v141, v47
	v_fmac_f32_e32 v148, v142, v50
	v_fmac_f32_e32 v149, v142, v54
	v_fmac_f32_e32 v150, v142, v58
	v_fmac_f32_e32 v151, v142, v62
	v_fmac_f32_e32 v152, v142, v66
	v_fmac_f32_e32 v153, v142, v2
	v_fmac_f32_e32 v154, v142, v6
	v_fmac_f32_e32 v155, v142, v10
	v_fmac_f32_e32 v156, v142, v14
	v_fmac_f32_e32 v157, v142, v18
	v_fmac_f32_e32 v158, v142, v22
	v_fmac_f32_e32 v159, v142, v26
	v_fmac_f32_e32 v160, v142, v30
	v_fmac_f32_e32 v161, v142, v34
	v_fmac_f32_e32 v162, v142, v38
	v_fmac_f32_e32 v163, v142, v70
	v_fmac_f32_e32 v164, v142, v74
	v_fmac_f32_e32 v165, v142, v78
	v_fmac_f32_e32 v166, v142, v82
	v_fmac_f32_e32 v167, v142, v86
	v_fmac_f32_e32 v168, v142, v90
	v_fmac_f32_e32 v169, v142, v94
	v_fmac_f32_e32 v170, v142, v98
	v_fmac_f32_e32 v171, v142, v102
	v_fmac_f32_e32 v172, v142, v106
	v_fmac_f32_e32 v173, v142, v110
	v_fmac_f32_e32 v174, v142, v114
	v_fmac_f32_e32 v175, v142, v118
	v_fmac_f32_e32 v176, v142, v122
	v_fmac_f32_e32 v177, v142, v188
	v_fmac_f32_e32 v178, v142, v184
	s_waitcnt lgkmcnt(0)
	v_fmac_f32_e32 v179, v142, v180
	v_fmac_f32_e32 v139, v140, v44
	v_fmac_f32_e32 v147, v140, v48
	v_fmac_f32_e32 v148, v141, v51
	v_fmac_f32_e32 v149, v141, v55
	v_fmac_f32_e32 v150, v141, v59
	v_fmac_f32_e32 v151, v141, v63
	v_fmac_f32_e32 v152, v141, v67
	v_fmac_f32_e32 v153, v141, v3
	v_fmac_f32_e32 v154, v141, v7
	v_fmac_f32_e32 v155, v141, v11
	v_fmac_f32_e32 v156, v141, v15
	v_fmac_f32_e32 v157, v141, v19
	v_fmac_f32_e32 v158, v141, v23
	v_fmac_f32_e32 v159, v141, v27
	v_fmac_f32_e32 v160, v141, v31
	v_fmac_f32_e32 v161, v141, v35
	v_fmac_f32_e32 v162, v141, v39
	v_fmac_f32_e32 v163, v141, v71
	v_fmac_f32_e32 v164, v141, v75
	v_fmac_f32_e32 v165, v141, v79
	v_fmac_f32_e32 v166, v141, v83
	v_fmac_f32_e32 v167, v141, v87
	v_fmac_f32_e32 v168, v141, v91
	v_fmac_f32_e32 v169, v141, v95
	v_fmac_f32_e32 v170, v141, v99
	v_fmac_f32_e32 v171, v141, v103
	v_fmac_f32_e32 v172, v141, v107
	v_fmac_f32_e32 v173, v141, v111
	v_fmac_f32_e32 v174, v141, v115
	v_fmac_f32_e32 v175, v141, v119
	v_fmac_f32_e32 v176, v141, v123
	v_fmac_f32_e32 v177, v141, v189
	v_fmac_f32_e32 v178, v141, v185
	v_fmac_f32_e32 v179, v141, v181
	v_fmac_f32_e32 v139, v128, v45
	v_fmac_f32_e32 v147, v128, v49
	v_fmac_f32_e32 v148, v140, v52
	v_fmac_f32_e32 v149, v140, v56
	v_fmac_f32_e32 v150, v140, v60
	v_fmac_f32_e32 v151, v140, v64
	v_fmac_f32_e32 v152, v140, v68
	v_fmac_f32_e32 v153, v140, v4
	v_fmac_f32_e32 v154, v140, v8
	v_fmac_f32_e32 v155, v140, v12
	v_fmac_f32_e32 v156, v140, v16
	v_fmac_f32_e32 v157, v140, v20
	v_fmac_f32_e32 v158, v140, v24
	v_fmac_f32_e32 v159, v140, v28
	v_fmac_f32_e32 v160, v140, v32
	v_fmac_f32_e32 v161, v140, v36
	v_fmac_f32_e32 v162, v140, v40
	v_fmac_f32_e32 v163, v140, v72
	v_fmac_f32_e32 v164, v140, v76
	v_fmac_f32_e32 v165, v140, v80
	v_fmac_f32_e32 v166, v140, v84
	v_fmac_f32_e32 v167, v140, v88
	v_fmac_f32_e32 v168, v140, v92
	v_fmac_f32_e32 v169, v140, v96
	v_fmac_f32_e32 v170, v140, v100
	v_fmac_f32_e32 v171, v140, v104
	v_fmac_f32_e32 v172, v140, v108
	v_fmac_f32_e32 v173, v140, v112
	v_fmac_f32_e32 v174, v140, v116
	v_fmac_f32_e32 v175, v140, v120
	v_fmac_f32_e32 v176, v140, v124
	v_fmac_f32_e32 v177, v140, v190
	v_fmac_f32_e32 v178, v140, v186
	v_fmac_f32_e32 v179, v140, v182
	v_fmac_f32_e32 v148, v128, v53
	v_fmac_f32_e32 v149, v128, v57
	v_fmac_f32_e32 v150, v128, v61
	v_fmac_f32_e32 v151, v128, v65
	v_fmac_f32_e32 v152, v128, v69
	v_fmac_f32_e32 v153, v128, v5
	v_fmac_f32_e32 v154, v128, v9
	v_fmac_f32_e32 v155, v128, v13
	v_fmac_f32_e32 v156, v128, v17
	v_fmac_f32_e32 v157, v128, v21
	v_fmac_f32_e32 v158, v128, v25
	v_fmac_f32_e32 v159, v128, v29
	v_fmac_f32_e32 v160, v128, v33
	v_fmac_f32_e32 v161, v128, v37
	v_fmac_f32_e32 v162, v128, v41
	v_fmac_f32_e32 v163, v128, v73
	v_fmac_f32_e32 v164, v128, v77
	v_fmac_f32_e32 v165, v128, v81
	v_fmac_f32_e32 v166, v128, v85
	v_fmac_f32_e32 v167, v128, v89
	v_fmac_f32_e32 v168, v128, v93
	v_fmac_f32_e32 v169, v128, v97
	v_fmac_f32_e32 v170, v128, v101
	v_fmac_f32_e32 v171, v128, v105
	v_fmac_f32_e32 v172, v128, v109
	v_fmac_f32_e32 v173, v128, v113
	v_fmac_f32_e32 v174, v128, v117
	v_fmac_f32_e32 v175, v128, v121
	v_fmac_f32_e32 v176, v128, v125
	v_fmac_f32_e32 v177, v128, v191
	v_fmac_f32_e32 v178, v128, v187
	v_fmac_f32_e32 v179, v128, v183
	ds_write2st64_b32 v138, v139, v147 offset0:144 offset1:145
	ds_write2st64_b32 v138, v148, v149 offset0:146 offset1:147
	ds_write2st64_b32 v138, v150, v151 offset0:148 offset1:149
	ds_write2st64_b32 v138, v152, v153 offset0:150 offset1:151
	ds_write2st64_b32 v138, v154, v155 offset0:152 offset1:153
	ds_write2st64_b32 v138, v156, v157 offset0:154 offset1:155
	ds_write2st64_b32 v138, v158, v159 offset0:156 offset1:157
	ds_write2st64_b32 v138, v160, v161 offset0:158 offset1:159
	ds_write2st64_b32 v138, v162, v163 offset0:160 offset1:161
	ds_write2st64_b32 v138, v164, v165 offset0:162 offset1:163
	ds_write2st64_b32 v138, v166, v167 offset0:164 offset1:165
	ds_write2st64_b32 v138, v168, v169 offset0:166 offset1:167
	ds_write2st64_b32 v138, v170, v171 offset0:168 offset1:169
	ds_write2st64_b32 v138, v172, v173 offset0:170 offset1:171
	ds_write2st64_b32 v138, v174, v175 offset0:172 offset1:173
	ds_write2st64_b32 v138, v176, v177 offset0:174 offset1:175
	ds_write2st64_b32 v138, v178, v179 offset0:176 offset1:177
	s_waitcnt lgkmcnt(0)
	s_barrier
	s_and_saveexec_b64 s[8:9], s[4:5]
	s_cbranch_execz .LBB0_138
	s_mul_i32 s7, s14, 0xc00
	v_or_b32_e32 v2, s6, v126
	v_add_u32_e32 v4, s7, v2
	v_readlane_b32 s36, v241, 18
	s_cmp_eq_u32 s12, 0
	v_ashrrev_i32_e32 v5, 31, v4
	v_ashrrev_i32_e32 v3, 31, v2
	v_readlane_b32 s42, v241, 24
	v_readlane_b32 s43, v241, 25
	s_cselect_b64 s[12:13], -1, 0
	s_mul_hi_i32 s15, s14, 34
	s_mul_i32 s14, s14, 34
	v_lshl_add_u64 v[2:3], v[2:3], 2, s[90:91]
	v_lshl_add_u64 v[4:5], v[4:5], 2, s[42:43]
	global_load_dword v242, v[4:5], off
	s_mov_b64 s[6:7], 0
	v_mov_b32_e32 v8, v1
	v_readlane_b32 s37, v241, 19
	v_readlane_b32 s38, v241, 20
	v_readlane_b32 s39, v241, 21
	v_readlane_b32 s40, v241, 22
	v_readlane_b32 s41, v241, 23
	v_readlane_b32 s44, v241, 26
	v_readlane_b32 s45, v241, 27
	v_readlane_b32 s46, v241, 28
	v_readlane_b32 s47, v241, 29
	v_readlane_b32 s48, v241, 30
	v_readlane_b32 s49, v241, 31
	v_readlane_b32 s50, v241, 32
	v_readlane_b32 s51, v241, 33
	s_waitcnt vmcnt(0)
	s_branch .LBB0_142

.LBB0_142:
	v_ashrrev_i32_e32 v6, 6, v8
	v_lshl_add_u32 v7, v6, 8, v136
	ds_read2st64_b32 v[10:11], v7 offset0:144 offset1:178
	v_add_u32_e32 v9, 0x9000, v7
	ds_read2st64_b32 v[12:13], v7 offset0:212 offset1:246
	ds_read2st64_b32 v[14:15], v9 offset0:136 offset1:170
	ds_read2st64_b32 v[16:17], v9 offset0:204 offset1:238
	s_andn2_b64 vcc, exec, s[12:13]
	s_waitcnt lgkmcnt(3)
	v_add_f32_e32 v7, 0, v10
	v_add_f32_e32 v7, v7, v11
	s_waitcnt lgkmcnt(2)
	v_add_f32_e32 v7, v7, v12
	v_add_f32_e32 v7, v7, v13
	s_waitcnt lgkmcnt(1)
	v_add_f32_e32 v7, v7, v14
	v_add_f32_e32 v7, v7, v15
	s_waitcnt lgkmcnt(0)
	v_add_f32_e32 v7, v7, v16
	v_add_f32_e32 v9, v7, v17
	s_cbranch_vccnz .LBB0_141
	v_add_f32_e32 v9, v9, v242
	s_branch .LBB0_141
